# grid barrier steady-state path hand-written: arrival add, XCD-last writes back and adds to top word, all workgroups poll the top word (one device-scope round trip and the integer divisions removed)
# speedup vs baseline: 1.0078x; 1.0078x over previous
_Z2mk6Paramsii:
	s_load_dwordx2 s[30:31], s[0:1], 0x138
	s_load_dword s42, s[0:1], 0x140
	s_mov_b64 s[74:75], s[0:1]
	s_add_u32 s80, s74, 0x140
	s_addc_u32 s81, s75, 0
	s_waitcnt lgkmcnt(0)
	s_sub_i32 s0, s31, s30
	s_mov_b32 s66, s2
	s_mov_b32 s101, 0
	s_cmp_lt_i32 s0, 2
	s_cbranch_scc1 .LBB0_5
	v_and_b32_e32 v1, 0x3ff, v0
	s_nop 0
	v_cmp_eq_u32_e32 vcc, 0, v1
	s_and_saveexec_b64 s[0:1], vcc
	s_cbranch_execz .LBB0_4
	s_add_i32 s2, 0, 0x10010
	v_mov_b32_e32 v2, 0
	s_mov_b64 s[4:5], exec
	v_mov_b32_e32 v3, v2
	v_mov_b32_e32 v4, v2
	v_mov_b32_e32 v5, v2
	v_mov_b32_e32 v1, s2
	ds_write_b128 v1, v[2:5]
	v_mbcnt_lo_u32_b32 v1, s4, 0
	v_mbcnt_hi_u32_b32 v1, s5, v1
	v_cmp_eq_u32_e32 vcc, 0, v1
	s_getreg_b32 s2, hwreg(HW_REG_XCC_ID, 0, 4)
	s_and_b64 s[6:7], exec, vcc
	s_mov_b64 exec, s[6:7]
	s_cbranch_execz .LBB0_4
	s_load_dwordx2 s[6:7], s[74:75], 0x130
	s_lshl_b32 s2, s2, 8
	s_and_b32 s2, s2, 0xf00
	v_mov_b32_e32 v1, 0x24000
	s_waitcnt lgkmcnt(0)
	s_add_u32 s2, s6, s2
	s_addc_u32 s3, s7, 0
	s_bcnt1_i32_b64 s4, s[4:5]
	v_mov_b32_e32 v2, s4
	global_atomic_add v1, v2, s[2:3] offset:1280

.LBB0_981:
	s_lshl_b32 s3, s3, 8
	s_add_u32 s8, s6, s3
	s_addc_u32 s9, s7, 0
	s_add_u32 s8, s8, 0x25500
	s_addc_u32 s9, s9, 0
	s_add_u32 s10, s6, 0x27500
	s_addc_u32 s11, s7, 0
	s_waitcnt lgkmcnt(0)
	v_readfirstlane_b32 s12, v3
	v_readfirstlane_b32 s13, v0
	v_mov_b32_e32 v2, 1
	global_atomic_add v4, v1, v2, s[8:9] sc0
	s_add_u32 s101, s101, 1
	s_mul_i32 s15, s101, s12
	s_waitcnt vmcnt(0)
	v_readfirstlane_b32 s14, v4
	s_add_u32 s14, s14, 1
	s_cmp_eq_u32 s14, s15
	s_cbranch_scc0 .Lxb_wait
	buffer_wbl2 sc1
	s_waitcnt vmcnt(0)
	global_atomic_add v1, v2, s[10:11]
.Lxb_wait:
	s_mul_i32 s15, s101, s13
.Lxb_spin:
	global_load_dword v4, v1, s[10:11] sc1
	s_waitcnt vmcnt(0)
	v_readfirstlane_b32 s14, v4
	s_cmp_ge_u32 s14, s15
	s_cbranch_scc1 .Lxb_done
	s_sleep 1
	s_branch .Lxb_spin
.Lxb_done:
	buffer_inv sc1
	s_waitcnt vmcnt(0)

	.amdhsa_kernel _Z2mk6Paramsii
		.amdhsa_group_segment_fixed_size 0
		.amdhsa_private_segment_fixed_size 0
		.amdhsa_kernarg_size 576
		.amdhsa_user_sgpr_count 2
		.amdhsa_user_sgpr_dispatch_ptr 0
		.amdhsa_user_sgpr_queue_ptr 0
		.amdhsa_user_sgpr_kernarg_segment_ptr 1
		.amdhsa_user_sgpr_dispatch_id 0
		.amdhsa_user_sgpr_kernarg_preload_length 0
		.amdhsa_user_sgpr_kernarg_preload_offset 0
		.amdhsa_user_sgpr_private_segment_size 0
		.amdhsa_uses_dynamic_stack 0
		.amdhsa_enable_private_segment 0
		.amdhsa_system_sgpr_workgroup_id_x 1
		.amdhsa_system_sgpr_workgroup_id_y 0
		.amdhsa_system_sgpr_workgroup_id_z 0
		.amdhsa_system_sgpr_workgroup_info 0
		.amdhsa_system_vgpr_workitem_id 2
		.amdhsa_next_free_vgpr 256
		.amdhsa_next_free_sgpr 102
		.amdhsa_accum_offset 256
		.amdhsa_reserve_vcc 1
		.amdhsa_float_round_mode_32 0
		.amdhsa_float_round_mode_16_64 0
		.amdhsa_float_denorm_mode_32 3
		.amdhsa_float_denorm_mode_16_64 3
		.amdhsa_dx10_clamp 1
		.amdhsa_ieee_mode 1
		.amdhsa_fp16_overflow 0
		.amdhsa_tg_split 0
		.amdhsa_exception_fp_ieee_invalid_op 0
		.amdhsa_exception_fp_denorm_src 0
		.amdhsa_exception_fp_ieee_div_zero 0
		.amdhsa_exception_fp_ieee_overflow 0
		.amdhsa_exception_fp_ieee_underflow 0
		.amdhsa_exception_fp_ieee_inexact 0
		.amdhsa_exception_int_div_zero 0
	.end_amdhsa_kernel
